# EpiResid (P7/P11/P13): dummy dword loads prefetch both halves' residual rows into L2 right after the gain wait; on top of P14 pipeline + P0 gain hoist
# baseline (speedup 1.0000x reference)
;     __device__ __forceinline__ void operator()(const Acc& acc, const Unit& u, int wr, int wc, int fr, int fq) const {
;         const int row0 = u.pm * BM + wr * 64 + fr, col0 = u.pn * BM + wc * 32 + 8 * fq;
;         f32x4 gv[2][2], gi[2][2];
; #pragma unroll
;         for (int bj = 0; bj < 2; ++bj)
; #pragma unroll
;             for (int n = 0; n < 2; ++n) { gv[bj][n] = *(const f32x4*)(gain + col0 + bj * HALF + 4 * n); const f32x4 gp = *(const f32x4*)(gprev + col0 + bj * HALF + 4 * n);
;                 gi[bj][n] = (f32x4){1.0f / gp[0], 1.0f / gp[1], 1.0f / gp[2], 1.0f / gp[3]}; }
; #pragma unroll
;         for (int ai = 0; ai < 2; ++ai) {
;             u32x4 pv[4][2]; float rinv[4];
; #pragma unroll
;             for (int m = 0; m < 4; ++m) { const int row = row0 + ai * HALF + m * 16; rinv[m] = rsprev ? rsprev[row] : 1.0f;
; #pragma unroll
;                 for (int bj = 0; bj < 2; ++bj) { const int cx = col0 + bj * HALF; pv[m][bj] = *(const u32x4*)(xs + ((size_t)(cx >> 6) * T + row) * 64 + (cx & 63)); } }
.LBB0_729:
	s_lshl_b32 s0, s76, 8
	s_or_b32 s6, s0, s50
	v_or_b32_e32 v88, s6, v217
	v_ashrrev_i32_e32 v89, 31, v88
	v_readlane_b32 s80, v251, 1
	v_lshlrev_b64 v[88:89], 2, v[88:89]
	v_readlane_b32 s92, v251, 13
	v_readlane_b32 s93, v251, 14
	v_readlane_b32 s81, v251, 2
	v_readlane_b32 s82, v251, 3
	v_lshl_add_u64 v[148:149], s[92:93], 0, v[88:89]
	global_load_dwordx4 v[112:115], v[148:149], off
	global_load_dwordx4 v[116:119], v[148:149], off offset:16
	v_readlane_b32 s83, v251, 4
	v_readlane_b32 s84, v251, 5
	v_readlane_b32 s85, v251, 6
	v_readlane_b32 s86, v251, 7
	v_readlane_b32 s87, v251, 8
	v_readlane_b32 s88, v251, 9
	v_readlane_b32 s89, v251, 10
	v_readlane_b32 s90, v251, 11
	v_readlane_b32 s91, v251, 12
	v_readlane_b32 s94, v251, 15
	v_readlane_b32 s95, v251, 16
	v_readlane_b32 s80, v251, 21
	v_readlane_b32 s92, v251, 33
	v_readlane_b32 s93, v251, 34
	v_lshl_add_u32 v206, s48, 8, v216
	v_ashrrev_i32_e32 v207, 31, v206
	v_lshl_add_u64 v[152:153], s[92:93], 0, v[88:89]
	global_load_dwordx4 v[88:91], v[152:153], off offset:16
	global_load_dwordx4 v[92:95], v[152:153], off
	global_load_dwordx4 v[144:147], v[148:149], off offset:528
	s_nop 0
	global_load_dwordx4 v[148:151], v[148:149], off offset:512
	v_lshlrev_b64 v[214:215], 7, v[206:207]
	v_readlane_b32 s81, v251, 22
	v_readlane_b32 s82, v251, 23
	v_readlane_b32 s83, v251, 24
	v_readlane_b32 s84, v251, 25
	v_readlane_b32 s85, v251, 26
	v_readlane_b32 s86, v251, 27
	v_readlane_b32 s87, v251, 28
	v_readlane_b32 s88, v251, 29
	v_readlane_b32 s89, v251, 30
	v_readlane_b32 s90, v251, 31
	v_readlane_b32 s91, v251, 32
	v_readlane_b32 s94, v251, 35
	v_readlane_b32 s95, v251, 36
	s_waitcnt vmcnt(0)
	v_bitop3_b32 v240, s6, 56, v217 bitop3:0xc8
	s_ashr_i32 s98, s6, 6
	v_lshlrev_b32_e32 v240, 1, v240
	s_ashr_i32 s99, s98, 31
	v_mov_b32_e32 v241, 0
	s_lshl_b64 s[98:99], s[98:99], 21
	v_lshl_add_u64 v[240:241], s[36:37], 0, v[240:241]
	v_lshl_add_u64 v[240:241], v[240:241], 0, v[214:215]
	v_lshl_add_u64 v[240:241], v[240:241], 0, s[98:99]
	s_mov_b32 s100, 0x1000
	s_mov_b32 s101, 0
	v_lshl_add_u64 v[242:243], v[240:241], 0, s[100:101]
	s_mov_b32 s100, 0x4000
	v_lshl_add_u64 v[244:245], v[240:241], 0, s[100:101]
	v_lshl_add_u64 v[246:247], v[242:243], 0, s[100:101]
	global_load_dword v248, v[240:241], off
	global_load_dword v248, v[240:241], off offset:2048
	global_load_dword v248, v[242:243], off
	global_load_dword v248, v[242:243], off offset:2048
	global_load_dword v248, v[244:245], off
	global_load_dword v248, v[244:245], off offset:2048
	global_load_dword v248, v[246:247], off
	global_load_dword v248, v[246:247], off offset:2048
	s_mov_b32 s100, 0x400000
	v_lshl_add_u64 v[240:241], v[240:241], 0, s[100:101]
	v_lshl_add_u64 v[242:243], v[242:243], 0, s[100:101]
	v_lshl_add_u64 v[244:245], v[244:245], 0, s[100:101]
	v_lshl_add_u64 v[246:247], v[246:247], 0, s[100:101]
	global_load_dword v248, v[240:241], off
	global_load_dword v248, v[240:241], off offset:2048
	global_load_dword v248, v[242:243], off
	global_load_dword v248, v[242:243], off offset:2048
	global_load_dword v248, v[244:245], off
	global_load_dword v248, v[244:245], off offset:2048
	global_load_dword v248, v[246:247], off
	global_load_dword v248, v[246:247], off offset:2048
	v_div_scale_f32 v154, s[0:1], v112, v112, 1.0
	v_div_scale_f32 v156, s[0:1], v113, v113, 1.0
	v_rcp_f32_e32 v176, v154
	v_div_scale_f32 v158, s[12:13], v114, v114, 1.0
	v_div_scale_f32 v166, s[22:23], v118, v118, 1.0
	v_rcp_f32_e32 v189, v156
	v_div_scale_f32 v160, s[14:15], v115, v115, 1.0
	v_rcp_f32_e32 v190, v158
	v_rcp_f32_e32 v196, v166
	v_div_scale_f32 v162, s[16:17], v116, v116, 1.0
	v_rcp_f32_e32 v191, v160
	v_div_scale_f32 v164, s[20:21], v117, v117, 1.0
	v_rcp_f32_e32 v192, v162
	v_fma_f32 v188, -v154, v176, 1.0
	v_div_scale_f32 v155, vcc, 1.0, v112, 1.0
	v_rcp_f32_e32 v193, v164
	v_fma_f32 v194, -v156, v189, 1.0
	v_fmac_f32_e32 v176, v188, v176
	v_div_scale_f32 v157, s[0:1], 1.0, v113, 1.0
	v_fma_f32 v195, -v158, v190, 1.0
	v_fma_f32 v200, -v166, v196, 1.0
	v_fmac_f32_e32 v189, v194, v189
	v_mul_f32_e32 v188, v155, v176
	v_div_scale_f32 v159, s[12:13], 1.0, v114, 1.0
	v_fma_f32 v197, -v160, v191, 1.0
	v_fmac_f32_e32 v190, v195, v190
	v_fmac_f32_e32 v196, v200, v196
	v_mul_f32_e32 v194, v157, v189
	v_fma_f32 v200, -v154, v188, v155
	v_div_scale_f32 v161, s[14:15], 1.0, v115, 1.0
	v_fma_f32 v198, -v162, v192, 1.0
	v_fmac_f32_e32 v191, v197, v191
	v_mul_f32_e32 v195, v159, v190
	v_fma_f32 v201, -v156, v194, v157
	v_fmac_f32_e32 v188, v200, v176
	v_div_scale_f32 v163, s[16:17], 1.0, v116, 1.0
	v_fma_f32 v199, -v164, v193, 1.0
	v_fmac_f32_e32 v192, v198, v192
	v_mul_f32_e32 v197, v161, v191
	v_fma_f32 v202, -v158, v195, v159
	v_fmac_f32_e32 v194, v201, v189
	v_fma_f32 v154, -v154, v188, v155
	v_div_scale_f32 v165, s[20:21], 1.0, v117, 1.0
	v_fmac_f32_e32 v193, v199, v193
	v_mul_f32_e32 v198, v163, v192
	v_fma_f32 v203, -v160, v197, v161
	v_fmac_f32_e32 v195, v202, v190
	v_fma_f32 v155, -v156, v194, v157
	v_div_fmas_f32 v154, v154, v176, v188
	s_mov_b64 vcc, s[0:1]
	v_mul_f32_e32 v199, v165, v193
	v_fma_f32 v204, -v162, v198, v163
	v_fmac_f32_e32 v197, v203, v191
	v_fma_f32 v156, -v158, v195, v159
	v_div_fixup_f32 v188, v154, v112, 1.0
	v_div_fmas_f32 v112, v155, v189, v194
	s_mov_b64 vcc, s[12:13]
	v_fma_f32 v205, -v164, v199, v165
	v_fmac_f32_e32 v198, v204, v192
	v_fma_f32 v157, -v160, v197, v161
	v_div_fixup_f32 v189, v112, v113, 1.0
	v_div_fmas_f32 v112, v156, v190, v195
	s_mov_b64 vcc, s[14:15]
	v_fmac_f32_e32 v199, v205, v193
	v_fma_f32 v158, -v162, v198, v163
	v_div_fixup_f32 v194, v112, v114, 1.0
	v_div_fmas_f32 v112, v157, v191, v197
;     __device__ __forceinline__ void operator()(const Acc& acc, const Unit& u, int wr, int wc, int fr, int fq) const {
;     ...
;             for (int n = 0; n < 2; ++n) { gv[bj][n] = *(const f32x4*)(gain + col0 + bj * HALF + 4 * n); const f32x4 gp = *(const f32x4*)(gprev + col0 + bj * HALF + 4 * n);
;                 gi[bj][n] = (f32x4){1.0f / gp[0], 1.0f / gp[1], 1.0f / gp[2], 1.0f / gp[3]}; }
; #pragma unroll
;         for (int ai = 0; ai < 2; ++ai) {
;             u32x4 pv[4][2]; float rinv[4];
; #pragma unroll
;             for (int m = 0; m < 4; ++m) { const int row = row0 + ai * HALF + m * 16; rinv[m] = rsprev ? rsprev[row] : 1.0f;
; #pragma unroll
;                 for (int bj = 0; bj < 2; ++bj) { const int cx = col0 + bj * HALF; pv[m][bj] = *(const u32x4*)(xs + ((size_t)(cx >> 6) * T + row) * 64 + (cx & 63)); } }
	s_mov_b64 vcc, s[16:17]
	v_fma_f32 v159, -v164, v199, v165
	v_div_fixup_f32 v195, v112, v115, 1.0
	v_div_fmas_f32 v112, v158, v192, v198
	s_mov_b64 vcc, s[20:21]
	v_div_scale_f32 v167, s[22:23], 1.0, v118, 1.0
	v_div_fixup_f32 v192, v112, v116, 1.0
	v_div_fmas_f32 v112, v159, v193, v199
	v_div_fixup_f32 v193, v112, v117, 1.0
	v_mul_f32_e32 v112, v167, v196
	v_div_scale_f32 v114, s[0:1], v119, v119, 1.0
	v_fma_f32 v113, -v166, v112, v167
	v_rcp_f32_e32 v115, v114
	v_fmac_f32_e32 v112, v113, v196
	v_fma_f32 v113, -v166, v112, v167
	s_mov_b64 vcc, s[22:23]
	v_div_fmas_f32 v112, v113, v196, v112
	v_div_fixup_f32 v196, v112, v118, 1.0
	v_fma_f32 v112, -v114, v115, 1.0
	v_fmac_f32_e32 v115, v112, v115
	v_div_scale_f32 v112, vcc, 1.0, v119, 1.0
	v_mul_f32_e32 v113, v112, v115
	v_div_scale_f32 v154, s[0:1], v148, v148, 1.0
	v_fma_f32 v116, -v114, v113, v112
	v_rcp_f32_e32 v155, v154
	v_fmac_f32_e32 v113, v116, v115
	v_fma_f32 v112, -v114, v113, v112
	v_div_fmas_f32 v112, v112, v115, v113
	v_div_fixup_f32 v197, v112, v119, 1.0
	global_load_dwordx4 v[112:115], v[152:153], off offset:528
	global_load_dwordx4 v[116:119], v[152:153], off offset:512
	v_fma_f32 v152, -v154, v155, 1.0
	v_fmac_f32_e32 v155, v152, v155
	v_div_scale_f32 v152, vcc, 1.0, v148, 1.0
	v_mul_f32_e32 v153, v152, v155
	v_fma_f32 v156, -v154, v153, v152
	v_fmac_f32_e32 v153, v156, v155
	v_fma_f32 v152, -v154, v153, v152
	v_div_scale_f32 v154, s[0:1], v149, v149, 1.0
	v_rcp_f32_e32 v156, v154
	v_div_fmas_f32 v152, v152, v155, v153
	v_div_fixup_f32 v190, v152, v148, 1.0
	v_fma_f32 v148, -v154, v156, 1.0
	v_fmac_f32_e32 v156, v148, v156
	v_div_scale_f32 v148, vcc, 1.0, v149, 1.0
	v_mul_f32_e32 v152, v148, v156
	v_fma_f32 v153, -v154, v152, v148
	v_fmac_f32_e32 v152, v153, v156
	v_div_scale_f32 v153, s[0:1], v150, v150, 1.0
	v_fma_f32 v148, -v154, v152, v148
	v_rcp_f32_e32 v154, v153
	v_div_fmas_f32 v148, v148, v156, v152
	v_div_fixup_f32 v191, v148, v149, 1.0
	v_fma_f32 v148, -v153, v154, 1.0
	v_fmac_f32_e32 v154, v148, v154
	v_div_scale_f32 v148, vcc, 1.0, v150, 1.0
	v_mul_f32_e32 v149, v148, v154
	v_fma_f32 v152, -v153, v149, v148
	v_fmac_f32_e32 v149, v152, v154
	v_div_scale_f32 v152, s[0:1], v151, v151, 1.0
	v_fma_f32 v148, -v153, v149, v148
	v_rcp_f32_e32 v153, v152
	v_div_fmas_f32 v148, v148, v154, v149
	v_div_fixup_f32 v198, v148, v150, 1.0
	v_fma_f32 v148, -v152, v153, 1.0
	v_fmac_f32_e32 v153, v148, v153
	v_div_scale_f32 v148, vcc, 1.0, v151, 1.0
	v_mul_f32_e32 v149, v148, v153
	v_fma_f32 v150, -v152, v149, v148
	v_fmac_f32_e32 v149, v150, v153
	v_div_scale_f32 v150, s[0:1], v144, v144, 1.0
	v_fma_f32 v148, -v152, v149, v148
	v_rcp_f32_e32 v152, v150
	v_div_fmas_f32 v148, v148, v153, v149
	v_div_fixup_f32 v199, v148, v151, 1.0
	v_div_scale_f32 v153, s[0:1], v145, v145, 1.0
	v_fma_f32 v148, -v150, v152, 1.0
	v_fmac_f32_e32 v152, v148, v152
	v_div_scale_f32 v148, vcc, 1.0, v144, 1.0
	v_mul_f32_e32 v149, v148, v152
	v_fma_f32 v151, -v150, v149, v148
	v_fmac_f32_e32 v149, v151, v152
	v_fma_f32 v148, -v150, v149, v148
	v_rcp_f32_e32 v154, v153
	v_div_fmas_f32 v148, v148, v152, v149
	v_div_fixup_f32 v200, v148, v144, 1.0
	v_bitop3_b32 v148, s6, 56, v217 bitop3:0xc8
	v_lshlrev_b32_e32 v176, 1, v148
	s_ashr_i32 s0, s6, 6
	v_fma_f32 v144, -v153, v154, 1.0
	v_lshl_add_u64 v[204:205], s[36:37], 0, v[176:177]
	s_ashr_i32 s1, s0, 31
	v_fmac_f32_e32 v154, v144, v154
	v_div_scale_f32 v144, vcc, 1.0, v145, 1.0
	s_lshl_b64 s[14:15], s[0:1], 21
	v_lshl_add_u64 v[148:149], v[204:205], 0, v[214:215]
	v_mul_f32_e32 v152, v144, v154
	v_lshl_add_u64 v[150:151], v[148:149], 0, s[14:15]
	global_load_dwordx4 v[226:229], v[150:151], off
	v_fma_f32 v150, -v153, v152, v144
	v_fmac_f32_e32 v152, v150, v154
	v_div_scale_f32 v150, s[6:7], v146, v146, 1.0
	v_rcp_f32_e32 v151, v150
	v_fma_f32 v144, -v153, v152, v144
	v_div_fmas_f32 v144, v144, v154, v152
	v_div_fixup_f32 v201, v144, v145, 1.0
	v_fma_f32 v144, -v150, v151, 1.0
	v_fmac_f32_e32 v151, v144, v151
	v_div_scale_f32 v144, vcc, 1.0, v146, 1.0
	v_mul_f32_e32 v145, v144, v151
	v_fma_f32 v152, -v150, v145, v144
	v_fmac_f32_e32 v145, v152, v151
	v_fma_f32 v144, -v150, v145, v144
	v_div_scale_f32 v150, s[6:7], v147, v147, 1.0
	v_rcp_f32_e32 v152, v150
	v_div_fmas_f32 v144, v144, v151, v145
	v_div_fixup_f32 v202, v144, v146, 1.0
	s_or_b32 s0, s0, 2
	v_fma_f32 v144, -v150, v152, 1.0
	v_fmac_f32_e32 v152, v144, v152
	v_div_scale_f32 v144, vcc, 1.0, v147, 1.0
	v_mul_f32_e32 v146, v144, v152
	v_fma_f32 v145, -v150, v146, v144
	s_ashr_i32 s1, s0, 31
	v_fmac_f32_e32 v146, v145, v152
	s_lshl_b64 s[16:17], s[0:1], 21
	v_fma_f32 v150, -v150, v146, v144
	v_lshl_add_u64 v[144:145], v[148:149], 0, s[16:17]
	global_load_dwordx4 v[230:233], v[144:145], off
	v_div_fmas_f32 v144, v150, v152, v146
	v_and_b32_e32 v145, 64, v222
	v_div_fixup_f32 v203, v144, v147, 1.0
	v_xor_b32_e32 v144, 16, v222
	v_add_u32_e32 v145, 64, v145
	v_cmp_lt_i32_e32 vcc, v144, v145
	s_lshl_b32 s0, s76, 2
	s_ashr_i32 s1, s0, 31
	v_cndmask_b32_e32 v144, v222, v144, vcc
	v_lshlrev_b32_e32 v223, 2, v144
	v_xor_b32_e32 v144, 32, v222
	v_cmp_lt_i32_e32 vcc, v144, v145
	s_add_u32 s6, s36, s14
	s_addc_u32 s7, s37, s15
	v_cndmask_b32_e32 v224, v222, v144, vcc
	v_or_b32_e32 v144, 16, v206
	v_ashrrev_i32_e32 v145, 31, v144
	v_lshlrev_b64 v[212:213], 7, v[144:145]
	v_lshl_add_u64 v[144:145], v[204:205], 0, v[212:213]
	v_lshl_add_u64 v[146:147], v[144:145], 0, s[14:15]
	v_lshl_add_u64 v[144:145], v[144:145], 0, s[16:17]
	global_load_dwordx4 v[164:167], v[146:147], off
	global_load_dwordx4 v[160:163], v[144:145], off
	v_or_b32_e32 v144, 32, v206
	v_ashrrev_i32_e32 v145, 31, v144
	v_lshlrev_b64 v[210:211], 7, v[144:145]
	v_lshl_add_u64 v[144:145], v[204:205], 0, v[210:211]
	v_lshl_add_u64 v[146:147], v[144:145], 0, s[14:15]
	v_lshl_add_u64 v[144:145], v[144:145], 0, s[16:17]
	global_load_dwordx4 v[156:159], v[146:147], off
	global_load_dwordx4 v[152:155], v[144:145], off
	v_or_b32_e32 v144, 48, v206
	v_ashrrev_i32_e32 v145, 31, v144
	v_lshlrev_b64 v[208:209], 7, v[144:145]
	v_lshl_add_u64 v[144:145], v[204:205], 0, v[208:209]
	v_lshl_add_u64 v[146:147], v[144:145], 0, s[14:15]
	v_lshl_add_u64 v[144:145], v[144:145], 0, s[16:17]
	global_load_dwordx4 v[148:151], v[146:147], off
	s_nop 0
	global_load_dwordx4 v[144:147], v[144:145], off
	v_lshl_add_u64 v[234:235], s[6:7], 0, v[214:215]
	v_lshl_add_u64 v[234:235], v[234:235], 0, v[176:177]
	v_lshlrev_b32_e32 v224, 2, v224
	s_add_u32 s12, s36, s16
	s_addc_u32 s13, s37, s17
	s_waitcnt vmcnt(7)
; __device__ __forceinline__ unsigned cvt_pk_bf16(float lo, float hi) { const f32x2 v = {lo, hi}; const bf16x2_t r = __builtin_convertvector(v, bf16x2_t); return __builtin_bit_cast(unsigned, r); }
; __device__ __forceinline__ float bf_lo(unsigned w) { return __uint_as_float(w << 16); }
; __device__ __forceinline__ float bf_hi(unsigned w) { return __uint_as_float(w & 0xffff0000u); }
;     __device__ __forceinline__ void operator()(const Acc& acc, const Unit& u, int wr, int wc, int fr, int fq) const {
;     ...
;             for (int m = 0; m < 4; ++m) { const int row = row0 + ai * HALF + m * 16; const float ri = rsprev ? 1.0f / rinv[m] : 1.0f; float s = 0.f;
; #pragma unroll
;                 for (int bj = 0; bj < 2; ++bj) { const int cx = col0 + bj * HALF; bf16_t* px = xs + ((size_t)(cx >> 6) * T + row) * 64 + (cx & 63); const u32x4 pw = pv[m][bj];
;                     const f32x4 x0 = (f32x4){bf_lo(pw.x), bf_hi(pw.x), bf_lo(pw.y), bf_hi(pw.y)} * gi[bj][0] * ri, x1 = (f32x4){bf_lo(pw.z), bf_hi(pw.z), bf_lo(pw.w), bf_hi(pw.w)} * gi[bj][1] * ri;
;                     const f32x4 y0 = x0 + acc[ai][bj][m][0] * alpha, y1 = x1 + acc[ai][bj][m][1] * alpha;
;                     s += (y0[0] * y0[0] + y0[1] * y0[1]) + (y0[2] * y0[2] + y0[3] * y0[3]) + (y1[0] * y1[0] + y1[1] * y1[1]) + (y1[2] * y1[2] + y1[3] * y1[3]);
;                     const f32x4 a = y0 * gv[bj][0], b = y1 * gv[bj][1]; u32x4 w; w.x = cvt_pk_bf16(a[0], a[1]); w.y = cvt_pk_bf16(a[2], a[3]); w.z = cvt_pk_bf16(b[0], b[1]); w.w = cvt_pk_bf16(b[2], b[3]);
;                     *(u32x4*)px = w; }
;                 s += __shfl_xor(s, 16); s += __shfl_xor(s, 32);
;                 if (fq == 0) ss[(size_t)row * 32 + u.pn * 4 + wc] = s; }
	v_lshlrev_b32_e32 v236, 16, v226
	v_and_b32_e32 v237, 0xffff0000, v226
	v_lshlrev_b32_e32 v226, 16, v227
	v_and_b32_e32 v227, 0xffff0000, v227
	v_pk_fma_f32 v[142:143], v[194:195], v[226:227], v[142:143]
	v_pk_fma_f32 v[140:141], v[188:189], v[236:237], v[140:141]
	v_lshlrev_b32_e32 v238, 16, v228
	v_and_b32_e32 v239, 0xffff0000, v228
	v_mul_f32_e32 v225, v141, v141
	v_mul_f32_e32 v226, v143, v143
	v_pk_fma_f32 v[136:137], v[192:193], v[238:239], v[136:137]
	v_fmac_f32_e32 v225, v140, v140
	v_fmac_f32_e32 v226, v142, v142
	v_lshlrev_b32_e32 v228, 16, v229
	v_and_b32_e32 v229, 0xffff0000, v229
	v_add_f32_e32 v225, v225, v226
	v_mul_f32_e32 v226, v137, v137
	v_pk_fma_f32 v[138:139], v[196:197], v[228:229], v[138:139]
	v_fmac_f32_e32 v226, v136, v136
	v_add_f32_e32 v225, v226, v225
	v_mul_f32_e32 v226, v139, v139
	v_fmac_f32_e32 v226, v138, v138
	v_add_f32_e32 v225, v226, v225
	v_pk_mul_f32 v[142:143], v[94:95], v[142:143]
	v_pk_mul_f32 v[140:141], v[92:93], v[140:141]
	v_pk_mul_f32 v[226:227], v[90:91], v[138:139]
	v_pk_mul_f32 v[138:139], v[88:89], v[136:137]
	v_cvt_pk_bf16_f32 v136, v140, v141
	v_cvt_pk_bf16_f32 v137, v142, v143
	v_cvt_pk_bf16_f32 v138, v138, v139
	v_cvt_pk_bf16_f32 v139, v226, v227
	global_store_dwordx4 v[234:235], v[136:139], off
	s_waitcnt vmcnt(7)
	v_lshlrev_b32_e32 v140, 16, v231
	v_lshlrev_b32_e32 v138, 16, v230
	v_and_b32_e32 v139, 0xffff0000, v230
	v_and_b32_e32 v141, 0xffff0000, v231
	v_pk_fma_f32 v[134:135], v[198:199], v[140:141], v[134:135]
	v_pk_fma_f32 v[132:133], v[190:191], v[138:139], v[132:133]
	v_lshlrev_b32_e32 v142, 16, v232
	v_and_b32_e32 v143, 0xffff0000, v232
	v_mul_f32_e32 v138, v133, v133
	v_mul_f32_e32 v139, v135, v135
	v_pk_fma_f32 v[128:129], v[200:201], v[142:143], v[128:129]
	v_fmac_f32_e32 v138, v132, v132
	v_fmac_f32_e32 v139, v134, v134
	v_lshlrev_b32_e32 v226, 16, v233
	v_and_b32_e32 v227, 0xffff0000, v233
	v_add_f32_e32 v138, v138, v139
	v_mul_f32_e32 v139, v129, v129
	v_pk_fma_f32 v[130:131], v[202:203], v[226:227], v[130:131]
	v_fmac_f32_e32 v139, v128, v128
	v_add_f32_e32 v138, v139, v138
	v_mul_f32_e32 v139, v131, v131
	v_fmac_f32_e32 v139, v130, v130
	v_add_f32_e32 v138, v139, v138
	v_add_f32_e32 v142, v225, v138
	ds_bpermute_b32 v143, v223, v142
	v_pk_mul_f32 v[140:141], v[112:113], v[128:129]
	v_lshl_add_u64 v[136:137], s[12:13], 0, v[214:215]
	v_pk_mul_f32 v[134:135], v[118:119], v[134:135]
	v_pk_mul_f32 v[132:133], v[116:117], v[132:133]
	s_waitcnt lgkmcnt(0)
	v_add_f32_e32 v128, v142, v143
	ds_bpermute_b32 v129, v224, v128
	v_pk_mul_f32 v[138:139], v[114:115], v[130:131]
	v_lshl_add_u64 v[136:137], v[136:137], 0, v[176:177]
	v_cvt_pk_bf16_f32 v130, v132, v133
	v_cvt_pk_bf16_f32 v131, v134, v135
	v_cvt_pk_bf16_f32 v132, v140, v141
	v_cvt_pk_bf16_f32 v133, v138, v139
	global_store_dwordx4 v[136:137], v[130:133], off
	s_and_saveexec_b64 s[20:21], s[8:9]
	s_cbranch_execz .LBB0_731
	v_lshl_add_u64 v[130:131], s[46:47], 0, v[214:215]
	v_lshl_add_u64 v[130:131], s[0:1], 2, v[130:131]
	s_lshl_b32 s48, s43, 2
	v_lshl_add_u64 v[130:131], v[130:131], 0, s[48:49]
	s_waitcnt lgkmcnt(0)
	v_add_f32_e32 v128, v128, v129
	global_store_dword v[130:131], v128, off

;     __device__ __forceinline__ void operator()(const Acc& acc, const Unit& u, int wr, int wc, int fr, int fq) const {
;         const int row0 = u.pm * BM + wr * 64 + fr, col0 = u.pn * BM + wc * 32 + 8 * fq;
;         f32x4 gv[2][2], gi[2][2];
; #pragma unroll
;         for (int bj = 0; bj < 2; ++bj)
; #pragma unroll
;             for (int n = 0; n < 2; ++n) { gv[bj][n] = *(const f32x4*)(gain + col0 + bj * HALF + 4 * n); const f32x4 gp = *(const f32x4*)(gprev + col0 + bj * HALF + 4 * n);
;                 gi[bj][n] = (f32x4){1.0f / gp[0], 1.0f / gp[1], 1.0f / gp[2], 1.0f / gp[3]}; }
; #pragma unroll
;         for (int ai = 0; ai < 2; ++ai) {
;             u32x4 pv[4][2]; float rinv[4];
; #pragma unroll
;             for (int m = 0; m < 4; ++m) { const int row = row0 + ai * HALF + m * 16; rinv[m] = rsprev ? rsprev[row] : 1.0f;
; #pragma unroll
;                 for (int bj = 0; bj < 2; ++bj) { const int cx = col0 + bj * HALF; pv[m][bj] = *(const u32x4*)(xs + ((size_t)(cx >> 6) * T + row) * 64 + (cx & 63)); } }
.LBB0_955:
	s_lshl_b32 s0, s74, 8
	s_or_b32 s6, s0, s51
	v_or_b32_e32 v88, s6, v217
	v_ashrrev_i32_e32 v89, 31, v88
	v_readlane_b32 s76, v251, 21
	v_lshlrev_b64 v[88:89], 2, v[88:89]
	v_readlane_b32 s88, v251, 33
	v_readlane_b32 s89, v251, 34
	v_readlane_b32 s77, v251, 22
	v_readlane_b32 s78, v251, 23
	v_lshl_add_u64 v[148:149], s[88:89], 0, v[88:89]
	global_load_dwordx4 v[112:115], v[148:149], off
	global_load_dwordx4 v[116:119], v[148:149], off offset:16
	v_readlane_b32 s79, v251, 24
	v_readlane_b32 s80, v251, 25
	v_readlane_b32 s81, v251, 26
	v_readlane_b32 s82, v251, 27
	v_readlane_b32 s83, v251, 28
	v_readlane_b32 s84, v251, 29
	v_readlane_b32 s85, v251, 30
	v_readlane_b32 s86, v251, 31
	v_readlane_b32 s87, v251, 32
	v_readlane_b32 s90, v251, 35
	v_readlane_b32 s91, v251, 36
	v_readlane_b32 s76, v251, 37
	v_readlane_b32 s82, v251, 43
	v_readlane_b32 s83, v251, 44
	v_lshl_add_u32 v206, s44, 8, v216
	v_ashrrev_i32_e32 v207, 31, v206
	v_lshl_add_u64 v[152:153], s[82:83], 0, v[88:89]
	global_load_dwordx4 v[88:91], v[152:153], off offset:16
	global_load_dwordx4 v[92:95], v[152:153], off
	global_load_dwordx4 v[144:147], v[148:149], off offset:528
	s_nop 0
	global_load_dwordx4 v[148:151], v[148:149], off offset:512
	v_lshlrev_b64 v[214:215], 7, v[206:207]
	v_readlane_b32 s77, v251, 38
	v_readlane_b32 s78, v251, 39
	v_readlane_b32 s79, v251, 40
	v_readlane_b32 s80, v251, 41
	v_readlane_b32 s81, v251, 42
	v_readlane_b32 s84, v251, 45
	v_readlane_b32 s85, v251, 46
	v_readlane_b32 s86, v251, 47
	v_readlane_b32 s87, v251, 48
	v_readlane_b32 s88, v251, 49
	v_readlane_b32 s89, v251, 50
	v_readlane_b32 s90, v251, 51
	v_readlane_b32 s91, v251, 52
	s_waitcnt vmcnt(0)
	v_bitop3_b32 v240, s6, 56, v217 bitop3:0xc8
	s_ashr_i32 s98, s6, 6
	v_lshlrev_b32_e32 v240, 1, v240
	s_ashr_i32 s99, s98, 31
	v_mov_b32_e32 v241, 0
	s_lshl_b64 s[98:99], s[98:99], 21
	v_lshl_add_u64 v[240:241], s[36:37], 0, v[240:241]
	v_lshl_add_u64 v[240:241], v[240:241], 0, v[214:215]
	v_lshl_add_u64 v[240:241], v[240:241], 0, s[98:99]
	s_mov_b32 s100, 0x1000
	s_mov_b32 s101, 0
	v_lshl_add_u64 v[242:243], v[240:241], 0, s[100:101]
	s_mov_b32 s100, 0x4000
	v_lshl_add_u64 v[244:245], v[240:241], 0, s[100:101]
	v_lshl_add_u64 v[246:247], v[242:243], 0, s[100:101]
	global_load_dword v248, v[240:241], off
	global_load_dword v248, v[240:241], off offset:2048
	global_load_dword v248, v[242:243], off
	global_load_dword v248, v[242:243], off offset:2048
	global_load_dword v248, v[244:245], off
	global_load_dword v248, v[244:245], off offset:2048
	global_load_dword v248, v[246:247], off
	global_load_dword v248, v[246:247], off offset:2048
	s_mov_b32 s100, 0x400000
	v_lshl_add_u64 v[240:241], v[240:241], 0, s[100:101]
	v_lshl_add_u64 v[242:243], v[242:243], 0, s[100:101]
	v_lshl_add_u64 v[244:245], v[244:245], 0, s[100:101]
	v_lshl_add_u64 v[246:247], v[246:247], 0, s[100:101]
	global_load_dword v248, v[240:241], off
	global_load_dword v248, v[240:241], off offset:2048
	global_load_dword v248, v[242:243], off
	global_load_dword v248, v[242:243], off offset:2048
	global_load_dword v248, v[244:245], off
	global_load_dword v248, v[244:245], off offset:2048
	global_load_dword v248, v[246:247], off
	global_load_dword v248, v[246:247], off offset:2048
	v_div_scale_f32 v154, s[0:1], v112, v112, 1.0
	v_div_scale_f32 v156, s[0:1], v113, v113, 1.0
	v_rcp_f32_e32 v176, v154
	v_div_scale_f32 v158, s[12:13], v114, v114, 1.0
	v_div_scale_f32 v166, s[22:23], v118, v118, 1.0
	v_rcp_f32_e32 v189, v156
	v_div_scale_f32 v160, s[14:15], v115, v115, 1.0
	v_rcp_f32_e32 v190, v158
	v_rcp_f32_e32 v196, v166
	v_div_scale_f32 v162, s[16:17], v116, v116, 1.0
	v_rcp_f32_e32 v191, v160
	v_div_scale_f32 v164, s[20:21], v117, v117, 1.0
	v_rcp_f32_e32 v192, v162
	v_fma_f32 v188, -v154, v176, 1.0
	v_div_scale_f32 v155, vcc, 1.0, v112, 1.0
	v_rcp_f32_e32 v193, v164
	v_fma_f32 v194, -v156, v189, 1.0
	v_fmac_f32_e32 v176, v188, v176
	v_div_scale_f32 v157, s[0:1], 1.0, v113, 1.0
	v_fma_f32 v195, -v158, v190, 1.0
	v_fma_f32 v200, -v166, v196, 1.0
	v_fmac_f32_e32 v189, v194, v189
	v_mul_f32_e32 v188, v155, v176
	v_div_scale_f32 v159, s[12:13], 1.0, v114, 1.0
	v_fma_f32 v197, -v160, v191, 1.0
	v_fmac_f32_e32 v190, v195, v190
	v_fmac_f32_e32 v196, v200, v196
	v_mul_f32_e32 v194, v157, v189
	v_fma_f32 v200, -v154, v188, v155
	v_div_scale_f32 v161, s[14:15], 1.0, v115, 1.0
	v_fma_f32 v198, -v162, v192, 1.0
	v_fmac_f32_e32 v191, v197, v191
	v_mul_f32_e32 v195, v159, v190
	v_fma_f32 v201, -v156, v194, v157
	v_fmac_f32_e32 v188, v200, v176
	v_div_scale_f32 v163, s[16:17], 1.0, v116, 1.0
	v_fma_f32 v199, -v164, v193, 1.0
	v_fmac_f32_e32 v192, v198, v192
	v_mul_f32_e32 v197, v161, v191
	v_fma_f32 v202, -v158, v195, v159
	v_fmac_f32_e32 v194, v201, v189
	v_fma_f32 v154, -v154, v188, v155
	v_div_scale_f32 v165, s[20:21], 1.0, v117, 1.0
	v_fmac_f32_e32 v193, v199, v193
	v_mul_f32_e32 v198, v163, v192
	v_fma_f32 v203, -v160, v197, v161
	v_fmac_f32_e32 v195, v202, v190
	v_fma_f32 v155, -v156, v194, v157
	v_div_fmas_f32 v154, v154, v176, v188
	s_mov_b64 vcc, s[0:1]
	v_mul_f32_e32 v199, v165, v193
	v_fma_f32 v204, -v162, v198, v163
	v_fmac_f32_e32 v197, v203, v191
	v_fma_f32 v156, -v158, v195, v159
	v_div_fixup_f32 v188, v154, v112, 1.0
	v_div_fmas_f32 v112, v155, v189, v194
	s_mov_b64 vcc, s[12:13]
	v_fma_f32 v205, -v164, v199, v165
	v_fmac_f32_e32 v198, v204, v192
	v_fma_f32 v157, -v160, v197, v161
	v_div_fixup_f32 v189, v112, v113, 1.0
	v_div_fmas_f32 v112, v156, v190, v195
	s_mov_b64 vcc, s[14:15]
	v_fmac_f32_e32 v199, v205, v193
	v_fma_f32 v158, -v162, v198, v163
	v_div_fixup_f32 v194, v112, v114, 1.0
	v_div_fmas_f32 v112, v157, v191, v197
;     __device__ __forceinline__ void operator()(const Acc& acc, const Unit& u, int wr, int wc, int fr, int fq) const {
;     ...
;             for (int n = 0; n < 2; ++n) { gv[bj][n] = *(const f32x4*)(gain + col0 + bj * HALF + 4 * n); const f32x4 gp = *(const f32x4*)(gprev + col0 + bj * HALF + 4 * n);
;                 gi[bj][n] = (f32x4){1.0f / gp[0], 1.0f / gp[1], 1.0f / gp[2], 1.0f / gp[3]}; }
; #pragma unroll
;         for (int ai = 0; ai < 2; ++ai) {
;             u32x4 pv[4][2]; float rinv[4];
; #pragma unroll
;             for (int m = 0; m < 4; ++m) { const int row = row0 + ai * HALF + m * 16; rinv[m] = rsprev ? rsprev[row] : 1.0f;
; #pragma unroll
;                 for (int bj = 0; bj < 2; ++bj) { const int cx = col0 + bj * HALF; pv[m][bj] = *(const u32x4*)(xs + ((size_t)(cx >> 6) * T + row) * 64 + (cx & 63)); } }
	s_mov_b64 vcc, s[16:17]
	v_fma_f32 v159, -v164, v199, v165
	v_div_fixup_f32 v195, v112, v115, 1.0
	v_div_fmas_f32 v112, v158, v192, v198
	s_mov_b64 vcc, s[20:21]
	v_div_scale_f32 v167, s[22:23], 1.0, v118, 1.0
	v_div_fixup_f32 v192, v112, v116, 1.0
	v_div_fmas_f32 v112, v159, v193, v199
	v_div_fixup_f32 v193, v112, v117, 1.0
	v_mul_f32_e32 v112, v167, v196
	v_div_scale_f32 v114, s[0:1], v119, v119, 1.0
	v_fma_f32 v113, -v166, v112, v167
	v_rcp_f32_e32 v115, v114
	v_fmac_f32_e32 v112, v113, v196
	v_fma_f32 v113, -v166, v112, v167
	s_mov_b64 vcc, s[22:23]
	v_div_fmas_f32 v112, v113, v196, v112
	v_div_fixup_f32 v196, v112, v118, 1.0
	v_fma_f32 v112, -v114, v115, 1.0
	v_fmac_f32_e32 v115, v112, v115
	v_div_scale_f32 v112, vcc, 1.0, v119, 1.0
	v_mul_f32_e32 v113, v112, v115
	v_div_scale_f32 v154, s[0:1], v148, v148, 1.0
	v_fma_f32 v116, -v114, v113, v112
	v_rcp_f32_e32 v155, v154
	v_fmac_f32_e32 v113, v116, v115
	v_fma_f32 v112, -v114, v113, v112
	v_div_fmas_f32 v112, v112, v115, v113
	v_div_fixup_f32 v197, v112, v119, 1.0
	global_load_dwordx4 v[112:115], v[152:153], off offset:528
	global_load_dwordx4 v[116:119], v[152:153], off offset:512
	v_fma_f32 v152, -v154, v155, 1.0
	v_fmac_f32_e32 v155, v152, v155
	v_div_scale_f32 v152, vcc, 1.0, v148, 1.0
	v_mul_f32_e32 v153, v152, v155
	v_fma_f32 v156, -v154, v153, v152
	v_fmac_f32_e32 v153, v156, v155
	v_fma_f32 v152, -v154, v153, v152
	v_div_scale_f32 v154, s[0:1], v149, v149, 1.0
	v_rcp_f32_e32 v156, v154
	v_div_fmas_f32 v152, v152, v155, v153
	v_div_fixup_f32 v190, v152, v148, 1.0
	v_fma_f32 v148, -v154, v156, 1.0
	v_fmac_f32_e32 v156, v148, v156
	v_div_scale_f32 v148, vcc, 1.0, v149, 1.0
	v_mul_f32_e32 v152, v148, v156
	v_fma_f32 v153, -v154, v152, v148
	v_fmac_f32_e32 v152, v153, v156
	v_div_scale_f32 v153, s[0:1], v150, v150, 1.0
	v_fma_f32 v148, -v154, v152, v148
	v_rcp_f32_e32 v154, v153
	v_div_fmas_f32 v148, v148, v156, v152
	v_div_fixup_f32 v191, v148, v149, 1.0
	v_fma_f32 v148, -v153, v154, 1.0
	v_fmac_f32_e32 v154, v148, v154
	v_div_scale_f32 v148, vcc, 1.0, v150, 1.0
	v_mul_f32_e32 v149, v148, v154
	v_fma_f32 v152, -v153, v149, v148
	v_fmac_f32_e32 v149, v152, v154
	v_div_scale_f32 v152, s[0:1], v151, v151, 1.0
	v_fma_f32 v148, -v153, v149, v148
	v_rcp_f32_e32 v153, v152
	v_div_fmas_f32 v148, v148, v154, v149
	v_div_fixup_f32 v198, v148, v150, 1.0
	v_fma_f32 v148, -v152, v153, 1.0
	v_fmac_f32_e32 v153, v148, v153
	v_div_scale_f32 v148, vcc, 1.0, v151, 1.0
	v_mul_f32_e32 v149, v148, v153
	v_fma_f32 v150, -v152, v149, v148
	v_fmac_f32_e32 v149, v150, v153
	v_div_scale_f32 v150, s[0:1], v144, v144, 1.0
	v_fma_f32 v148, -v152, v149, v148
	v_rcp_f32_e32 v152, v150
	v_div_fmas_f32 v148, v148, v153, v149
	v_div_fixup_f32 v199, v148, v151, 1.0
	v_div_scale_f32 v153, s[0:1], v145, v145, 1.0
	v_fma_f32 v148, -v150, v152, 1.0
	v_fmac_f32_e32 v152, v148, v152
	v_div_scale_f32 v148, vcc, 1.0, v144, 1.0
	v_mul_f32_e32 v149, v148, v152
	v_fma_f32 v151, -v150, v149, v148
	v_fmac_f32_e32 v149, v151, v152
	v_fma_f32 v148, -v150, v149, v148
	v_rcp_f32_e32 v154, v153
	v_div_fmas_f32 v148, v148, v152, v149
	v_div_fixup_f32 v200, v148, v144, 1.0
	v_bitop3_b32 v148, s6, 56, v217 bitop3:0xc8
	v_lshlrev_b32_e32 v176, 1, v148
	s_ashr_i32 s0, s6, 6
	v_fma_f32 v144, -v153, v154, 1.0
	v_lshl_add_u64 v[204:205], s[36:37], 0, v[176:177]
	s_ashr_i32 s1, s0, 31
	v_fmac_f32_e32 v154, v144, v154
	v_div_scale_f32 v144, vcc, 1.0, v145, 1.0
	s_lshl_b64 s[14:15], s[0:1], 21
	v_lshl_add_u64 v[148:149], v[204:205], 0, v[214:215]
	v_mul_f32_e32 v152, v144, v154
	v_lshl_add_u64 v[150:151], v[148:149], 0, s[14:15]
	global_load_dwordx4 v[226:229], v[150:151], off
	v_fma_f32 v150, -v153, v152, v144
	v_fmac_f32_e32 v152, v150, v154
	v_div_scale_f32 v150, s[6:7], v146, v146, 1.0
	v_rcp_f32_e32 v151, v150
	v_fma_f32 v144, -v153, v152, v144
	v_div_fmas_f32 v144, v144, v154, v152
	v_div_fixup_f32 v201, v144, v145, 1.0
	v_fma_f32 v144, -v150, v151, 1.0
	v_fmac_f32_e32 v151, v144, v151
	v_div_scale_f32 v144, vcc, 1.0, v146, 1.0
	v_mul_f32_e32 v145, v144, v151
	v_fma_f32 v152, -v150, v145, v144
	v_fmac_f32_e32 v145, v152, v151
	v_fma_f32 v144, -v150, v145, v144
	v_div_scale_f32 v150, s[6:7], v147, v147, 1.0
	v_rcp_f32_e32 v152, v150
	v_div_fmas_f32 v144, v144, v151, v145
	v_div_fixup_f32 v202, v144, v146, 1.0
	s_or_b32 s0, s0, 2
	v_fma_f32 v144, -v150, v152, 1.0
	v_fmac_f32_e32 v152, v144, v152
	v_div_scale_f32 v144, vcc, 1.0, v147, 1.0
	v_mul_f32_e32 v146, v144, v152
	v_fma_f32 v145, -v150, v146, v144
	s_ashr_i32 s1, s0, 31
	v_fmac_f32_e32 v146, v145, v152
	s_lshl_b64 s[16:17], s[0:1], 21
	v_fma_f32 v150, -v150, v146, v144
	v_lshl_add_u64 v[144:145], v[148:149], 0, s[16:17]
	global_load_dwordx4 v[230:233], v[144:145], off
	v_div_fmas_f32 v144, v150, v152, v146
	v_and_b32_e32 v145, 64, v222
	v_div_fixup_f32 v203, v144, v147, 1.0
	v_xor_b32_e32 v144, 16, v222
	v_add_u32_e32 v145, 64, v145
	v_cmp_lt_i32_e32 vcc, v144, v145
	s_lshl_b32 s0, s74, 2
	s_ashr_i32 s1, s0, 31
	v_cndmask_b32_e32 v144, v222, v144, vcc
	v_lshlrev_b32_e32 v223, 2, v144
	v_xor_b32_e32 v144, 32, v222
	v_cmp_lt_i32_e32 vcc, v144, v145
	s_add_u32 s6, s36, s14
	s_addc_u32 s7, s37, s15
	v_cndmask_b32_e32 v224, v222, v144, vcc
	v_or_b32_e32 v144, 16, v206
	v_ashrrev_i32_e32 v145, 31, v144
	v_lshlrev_b64 v[212:213], 7, v[144:145]
	v_lshl_add_u64 v[144:145], v[204:205], 0, v[212:213]
	v_lshl_add_u64 v[146:147], v[144:145], 0, s[14:15]
	v_lshl_add_u64 v[144:145], v[144:145], 0, s[16:17]
	global_load_dwordx4 v[164:167], v[146:147], off
	global_load_dwordx4 v[160:163], v[144:145], off
	v_or_b32_e32 v144, 32, v206
	v_ashrrev_i32_e32 v145, 31, v144
	v_lshlrev_b64 v[210:211], 7, v[144:145]
	v_lshl_add_u64 v[144:145], v[204:205], 0, v[210:211]
	v_lshl_add_u64 v[146:147], v[144:145], 0, s[14:15]
	v_lshl_add_u64 v[144:145], v[144:145], 0, s[16:17]
	global_load_dwordx4 v[156:159], v[146:147], off
	global_load_dwordx4 v[152:155], v[144:145], off
	v_or_b32_e32 v144, 48, v206
	v_ashrrev_i32_e32 v145, 31, v144
	v_lshlrev_b64 v[208:209], 7, v[144:145]
	v_lshl_add_u64 v[144:145], v[204:205], 0, v[208:209]
	v_lshl_add_u64 v[146:147], v[144:145], 0, s[14:15]
	v_lshl_add_u64 v[144:145], v[144:145], 0, s[16:17]
	global_load_dwordx4 v[148:151], v[146:147], off
	s_nop 0
	global_load_dwordx4 v[144:147], v[144:145], off
	v_lshl_add_u64 v[234:235], s[6:7], 0, v[214:215]
	v_lshl_add_u64 v[234:235], v[234:235], 0, v[176:177]
	v_lshlrev_b32_e32 v224, 2, v224
	s_add_u32 s12, s36, s16
	s_addc_u32 s13, s37, s17
	s_waitcnt vmcnt(7)
; __device__ __forceinline__ unsigned cvt_pk_bf16(float lo, float hi) { const f32x2 v = {lo, hi}; const bf16x2_t r = __builtin_convertvector(v, bf16x2_t); return __builtin_bit_cast(unsigned, r); }
; __device__ __forceinline__ float bf_lo(unsigned w) { return __uint_as_float(w << 16); }
; __device__ __forceinline__ float bf_hi(unsigned w) { return __uint_as_float(w & 0xffff0000u); }
;     __device__ __forceinline__ void operator()(const Acc& acc, const Unit& u, int wr, int wc, int fr, int fq) const {
;     ...
;             for (int m = 0; m < 4; ++m) { const int row = row0 + ai * HALF + m * 16; const float ri = rsprev ? 1.0f / rinv[m] : 1.0f; float s = 0.f;
; #pragma unroll
;                 for (int bj = 0; bj < 2; ++bj) { const int cx = col0 + bj * HALF; bf16_t* px = xs + ((size_t)(cx >> 6) * T + row) * 64 + (cx & 63); const u32x4 pw = pv[m][bj];
;                     const f32x4 x0 = (f32x4){bf_lo(pw.x), bf_hi(pw.x), bf_lo(pw.y), bf_hi(pw.y)} * gi[bj][0] * ri, x1 = (f32x4){bf_lo(pw.z), bf_hi(pw.z), bf_lo(pw.w), bf_hi(pw.w)} * gi[bj][1] * ri;
;                     const f32x4 y0 = x0 + acc[ai][bj][m][0] * alpha, y1 = x1 + acc[ai][bj][m][1] * alpha;
;                     s += (y0[0] * y0[0] + y0[1] * y0[1]) + (y0[2] * y0[2] + y0[3] * y0[3]) + (y1[0] * y1[0] + y1[1] * y1[1]) + (y1[2] * y1[2] + y1[3] * y1[3]);
;                     const f32x4 a = y0 * gv[bj][0], b = y1 * gv[bj][1]; u32x4 w; w.x = cvt_pk_bf16(a[0], a[1]); w.y = cvt_pk_bf16(a[2], a[3]); w.z = cvt_pk_bf16(b[0], b[1]); w.w = cvt_pk_bf16(b[2], b[3]);
;                     *(u32x4*)px = w; }
;                 s += __shfl_xor(s, 16); s += __shfl_xor(s, 32);
;                 if (fq == 0) ss[(size_t)row * 32 + u.pn * 4 + wc] = s; }
	v_lshlrev_b32_e32 v236, 16, v226
	v_and_b32_e32 v237, 0xffff0000, v226
	v_lshlrev_b32_e32 v226, 16, v227
	v_and_b32_e32 v227, 0xffff0000, v227
	v_pk_fma_f32 v[142:143], v[194:195], v[226:227], v[142:143]
	v_pk_fma_f32 v[140:141], v[188:189], v[236:237], v[140:141]
	v_lshlrev_b32_e32 v238, 16, v228
	v_and_b32_e32 v239, 0xffff0000, v228
	v_mul_f32_e32 v225, v141, v141
	v_mul_f32_e32 v226, v143, v143
	v_pk_fma_f32 v[136:137], v[192:193], v[238:239], v[136:137]
	v_fmac_f32_e32 v225, v140, v140
	v_fmac_f32_e32 v226, v142, v142
	v_lshlrev_b32_e32 v228, 16, v229
	v_and_b32_e32 v229, 0xffff0000, v229
	v_add_f32_e32 v225, v225, v226
	v_mul_f32_e32 v226, v137, v137
	v_pk_fma_f32 v[138:139], v[196:197], v[228:229], v[138:139]
	v_fmac_f32_e32 v226, v136, v136
	v_add_f32_e32 v225, v226, v225
	v_mul_f32_e32 v226, v139, v139
	v_fmac_f32_e32 v226, v138, v138
	v_add_f32_e32 v225, v226, v225
	v_pk_mul_f32 v[142:143], v[94:95], v[142:143]
	v_pk_mul_f32 v[140:141], v[92:93], v[140:141]
	v_pk_mul_f32 v[226:227], v[90:91], v[138:139]
	v_pk_mul_f32 v[138:139], v[88:89], v[136:137]
	v_cvt_pk_bf16_f32 v136, v140, v141
	v_cvt_pk_bf16_f32 v137, v142, v143
	v_cvt_pk_bf16_f32 v138, v138, v139
	v_cvt_pk_bf16_f32 v139, v226, v227
	global_store_dwordx4 v[234:235], v[136:139], off
	s_waitcnt vmcnt(7)
	v_lshlrev_b32_e32 v140, 16, v231
	v_lshlrev_b32_e32 v138, 16, v230
	v_and_b32_e32 v139, 0xffff0000, v230
	v_and_b32_e32 v141, 0xffff0000, v231
	v_pk_fma_f32 v[134:135], v[198:199], v[140:141], v[134:135]
	v_pk_fma_f32 v[132:133], v[190:191], v[138:139], v[132:133]
	v_lshlrev_b32_e32 v142, 16, v232
	v_and_b32_e32 v143, 0xffff0000, v232
	v_mul_f32_e32 v138, v133, v133
	v_mul_f32_e32 v139, v135, v135
	v_pk_fma_f32 v[128:129], v[200:201], v[142:143], v[128:129]
	v_fmac_f32_e32 v138, v132, v132
	v_fmac_f32_e32 v139, v134, v134
	v_lshlrev_b32_e32 v226, 16, v233
	v_and_b32_e32 v227, 0xffff0000, v233
	v_add_f32_e32 v138, v138, v139
	v_mul_f32_e32 v139, v129, v129
	v_pk_fma_f32 v[130:131], v[202:203], v[226:227], v[130:131]
	v_fmac_f32_e32 v139, v128, v128
	v_add_f32_e32 v138, v139, v138
	v_mul_f32_e32 v139, v131, v131
	v_fmac_f32_e32 v139, v130, v130
	v_add_f32_e32 v138, v139, v138
	v_add_f32_e32 v142, v225, v138
	ds_bpermute_b32 v143, v223, v142
	v_pk_mul_f32 v[140:141], v[112:113], v[128:129]
	v_lshl_add_u64 v[136:137], s[12:13], 0, v[214:215]
	v_pk_mul_f32 v[134:135], v[118:119], v[134:135]
	v_pk_mul_f32 v[132:133], v[116:117], v[132:133]
	s_waitcnt lgkmcnt(0)
	v_add_f32_e32 v128, v142, v143
	ds_bpermute_b32 v129, v224, v128
	v_pk_mul_f32 v[138:139], v[114:115], v[130:131]
	v_lshl_add_u64 v[136:137], v[136:137], 0, v[176:177]
	v_cvt_pk_bf16_f32 v130, v132, v133
	v_cvt_pk_bf16_f32 v131, v134, v135
	v_cvt_pk_bf16_f32 v132, v140, v141
	v_cvt_pk_bf16_f32 v133, v138, v139
	global_store_dwordx4 v[136:137], v[130:133], off
	s_and_saveexec_b64 s[20:21], s[8:9]
	s_cbranch_execz .LBB0_957
	v_lshl_add_u64 v[130:131], s[40:41], 0, v[214:215]
	v_lshl_add_u64 v[130:131], s[0:1], 2, v[130:131]
	s_lshl_b32 s44, s50, 2
	v_lshl_add_u64 v[130:131], v[130:131], 0, s[44:45]
	s_waitcnt lgkmcnt(0)
	v_add_f32_e32 v128, v128, v129
	global_store_dword v[130:131], v128, off

;     __device__ __forceinline__ void operator()(const Acc& acc, const Unit& u, int wr, int wc, int fr, int fq) const {
;         const int row0 = u.pm * BM + wr * 64 + fr, col0 = u.pn * BM + wc * 32 + 8 * fq;
;         f32x4 gv[2][2], gi[2][2];
; #pragma unroll
;         for (int bj = 0; bj < 2; ++bj)
; #pragma unroll
;             for (int n = 0; n < 2; ++n) { gv[bj][n] = *(const f32x4*)(gain + col0 + bj * HALF + 4 * n); const f32x4 gp = *(const f32x4*)(gprev + col0 + bj * HALF + 4 * n);
;                 gi[bj][n] = (f32x4){1.0f / gp[0], 1.0f / gp[1], 1.0f / gp[2], 1.0f / gp[3]}; }
; #pragma unroll
;         for (int ai = 0; ai < 2; ++ai) {
;             u32x4 pv[4][2]; float rinv[4];
; #pragma unroll
;             for (int m = 0; m < 4; ++m) { const int row = row0 + ai * HALF + m * 16; rinv[m] = rsprev ? rsprev[row] : 1.0f;
; #pragma unroll
;                 for (int bj = 0; bj < 2; ++bj) { const int cx = col0 + bj * HALF; pv[m][bj] = *(const u32x4*)(xs + ((size_t)(cx >> 6) * T + row) * 64 + (cx & 63)); } }
.LBB0_1157:
	s_lshl_b32 s0, s66, 8
	s_or_b32 s57, s0, s42
	v_or_b32_e32 v80, s57, v217
	v_readlane_b32 s68, v251, 37
	v_ashrrev_i32_e32 v81, 31, v80
	v_readlane_b32 s70, v251, 39
	v_readlane_b32 s71, v251, 40
	v_readlane_b32 s74, v251, 43
	v_readlane_b32 s75, v251, 44
	v_lshlrev_b64 v[80:81], 2, v[80:81]
	s_mov_b64 s[70:71], s[74:75]
	v_lshl_add_u64 v[148:149], s[70:71], 0, v[80:81]
	global_load_dwordx4 v[104:107], v[148:149], off
	global_load_dwordx4 v[108:111], v[148:149], off offset:16
	v_readlane_b32 s78, v251, 47
	v_readlane_b32 s79, v251, 48
	v_readlane_b32 s82, v251, 51
	v_readlane_b32 s83, v251, 52
	s_mov_b64 s[78:79], s[82:83]
	v_lshl_add_u64 v[152:153], s[78:79], 0, v[80:81]
	global_load_dwordx4 v[80:83], v[152:153], off offset:16
	global_load_dwordx4 v[84:87], v[152:153], off
	global_load_dwordx4 v[144:147], v[148:149], off offset:528
	s_nop 0
	global_load_dwordx4 v[148:151], v[148:149], off offset:512
	v_lshl_add_u32 v206, s22, 8, v216
	v_ashrrev_i32_e32 v207, 31, v206
	v_lshlrev_b64 v[214:215], 7, v[206:207]
	v_readlane_b32 s69, v251, 38
	v_readlane_b32 s72, v251, 41
	v_readlane_b32 s73, v251, 42
	v_readlane_b32 s76, v251, 45
	v_readlane_b32 s77, v251, 46
	v_readlane_b32 s80, v251, 49
	v_readlane_b32 s81, v251, 50
	s_waitcnt vmcnt(0)
	v_bitop3_b32 v240, s57, 56, v217 bitop3:0xc8
	s_ashr_i32 s98, s57, 6
	v_lshlrev_b32_e32 v240, 1, v240
	s_ashr_i32 s99, s98, 31
	v_mov_b32_e32 v241, 0
	s_lshl_b64 s[98:99], s[98:99], 21
	v_lshl_add_u64 v[240:241], s[36:37], 0, v[240:241]
	v_lshl_add_u64 v[240:241], v[240:241], 0, v[214:215]
	v_lshl_add_u64 v[240:241], v[240:241], 0, s[98:99]
	s_mov_b32 s100, 0x1000
	s_mov_b32 s101, 0
	v_lshl_add_u64 v[242:243], v[240:241], 0, s[100:101]
	s_mov_b32 s100, 0x4000
	v_lshl_add_u64 v[244:245], v[240:241], 0, s[100:101]
	v_lshl_add_u64 v[246:247], v[242:243], 0, s[100:101]
	global_load_dword v248, v[240:241], off
	global_load_dword v248, v[240:241], off offset:2048
	global_load_dword v248, v[242:243], off
	global_load_dword v248, v[242:243], off offset:2048
	global_load_dword v248, v[244:245], off
	global_load_dword v248, v[244:245], off offset:2048
	global_load_dword v248, v[246:247], off
	global_load_dword v248, v[246:247], off offset:2048
	s_mov_b32 s100, 0x400000
	v_lshl_add_u64 v[240:241], v[240:241], 0, s[100:101]
	v_lshl_add_u64 v[242:243], v[242:243], 0, s[100:101]
	v_lshl_add_u64 v[244:245], v[244:245], 0, s[100:101]
	v_lshl_add_u64 v[246:247], v[246:247], 0, s[100:101]
	global_load_dword v248, v[240:241], off
	global_load_dword v248, v[240:241], off offset:2048
	global_load_dword v248, v[242:243], off
	global_load_dword v248, v[242:243], off offset:2048
	global_load_dword v248, v[244:245], off
	global_load_dword v248, v[244:245], off offset:2048
	global_load_dword v248, v[246:247], off
	global_load_dword v248, v[246:247], off offset:2048
	v_div_scale_f32 v154, s[0:1], v104, v104, 1.0
	v_div_scale_f32 v156, s[0:1], v105, v105, 1.0
	v_rcp_f32_e32 v176, v154
	v_div_scale_f32 v158, s[8:9], v106, v106, 1.0
	v_div_scale_f32 v166, s[16:17], v110, v110, 1.0
	v_rcp_f32_e32 v188, v156
	v_div_scale_f32 v160, s[10:11], v107, v107, 1.0
	v_rcp_f32_e32 v189, v158
	v_rcp_f32_e32 v197, v166
	v_div_scale_f32 v162, s[12:13], v108, v108, 1.0
	v_rcp_f32_e32 v192, v160
	v_div_scale_f32 v164, s[14:15], v109, v109, 1.0
	v_rcp_f32_e32 v193, v162
	v_fma_f32 v190, -v154, v176, 1.0
	v_div_scale_f32 v155, vcc, 1.0, v104, 1.0
	v_rcp_f32_e32 v196, v164
	v_fma_f32 v191, -v156, v188, 1.0
	v_fmac_f32_e32 v176, v190, v176
	v_div_scale_f32 v157, s[0:1], 1.0, v105, 1.0
	v_fma_f32 v194, -v158, v189, 1.0
	v_fma_f32 v200, -v166, v197, 1.0
	v_fmac_f32_e32 v188, v191, v188
	v_mul_f32_e32 v190, v155, v176
	v_div_scale_f32 v159, s[8:9], 1.0, v106, 1.0
	v_fma_f32 v195, -v160, v192, 1.0
	v_fmac_f32_e32 v189, v194, v189
	v_fmac_f32_e32 v197, v200, v197
	v_mul_f32_e32 v191, v157, v188
	v_fma_f32 v200, -v154, v190, v155
	v_div_scale_f32 v161, s[10:11], 1.0, v107, 1.0
	v_fma_f32 v198, -v162, v193, 1.0
	v_fmac_f32_e32 v192, v195, v192
	v_mul_f32_e32 v194, v159, v189
	v_fma_f32 v201, -v156, v191, v157
	v_fmac_f32_e32 v190, v200, v176
	v_div_scale_f32 v163, s[12:13], 1.0, v108, 1.0
	v_fma_f32 v199, -v164, v196, 1.0
	v_fmac_f32_e32 v193, v198, v193
	v_mul_f32_e32 v195, v161, v192
	v_fma_f32 v202, -v158, v194, v159
	v_fmac_f32_e32 v191, v201, v188
	v_fma_f32 v154, -v154, v190, v155
	v_div_scale_f32 v165, s[14:15], 1.0, v109, 1.0
	v_fmac_f32_e32 v196, v199, v196
	v_mul_f32_e32 v198, v163, v193
	v_fma_f32 v203, -v160, v195, v161
	v_fmac_f32_e32 v194, v202, v189
	v_fma_f32 v155, -v156, v191, v157
	v_div_fmas_f32 v154, v154, v176, v190
	s_mov_b64 vcc, s[0:1]
	v_mul_f32_e32 v199, v165, v196
	v_fma_f32 v204, -v162, v198, v163
	v_fmac_f32_e32 v195, v203, v192
	v_fma_f32 v156, -v158, v194, v159
	v_div_fixup_f32 v190, v154, v104, 1.0
	v_div_fmas_f32 v104, v155, v188, v191
	s_mov_b64 vcc, s[8:9]
	v_fma_f32 v205, -v164, v199, v165
	v_fmac_f32_e32 v198, v204, v193
	v_fma_f32 v157, -v160, v195, v161
	v_div_fixup_f32 v191, v104, v105, 1.0
	v_div_fmas_f32 v104, v156, v189, v194
	s_mov_b64 vcc, s[10:11]
	v_fmac_f32_e32 v199, v205, v196
	v_fma_f32 v158, -v162, v198, v163
	v_div_fixup_f32 v194, v104, v106, 1.0
	v_div_fmas_f32 v104, v157, v192, v195
	s_mov_b64 vcc, s[12:13]
	v_fma_f32 v159, -v164, v199, v165
	v_div_fixup_f32 v195, v104, v107, 1.0
	v_div_fmas_f32 v104, v158, v193, v198
	s_mov_b64 vcc, s[14:15]
	v_div_scale_f32 v167, s[16:17], 1.0, v110, 1.0
	v_div_fixup_f32 v192, v104, v108, 1.0
	v_div_fmas_f32 v104, v159, v196, v199
	v_div_fixup_f32 v193, v104, v109, 1.0
	v_mul_f32_e32 v104, v167, v197
	v_div_scale_f32 v106, s[0:1], v111, v111, 1.0
;     __device__ __forceinline__ void operator()(const Acc& acc, const Unit& u, int wr, int wc, int fr, int fq) const {
;     ...
;             for (int n = 0; n < 2; ++n) { gv[bj][n] = *(const f32x4*)(gain + col0 + bj * HALF + 4 * n); const f32x4 gp = *(const f32x4*)(gprev + col0 + bj * HALF + 4 * n);
;                 gi[bj][n] = (f32x4){1.0f / gp[0], 1.0f / gp[1], 1.0f / gp[2], 1.0f / gp[3]}; }
; #pragma unroll
;         for (int ai = 0; ai < 2; ++ai) {
;             u32x4 pv[4][2]; float rinv[4];
; #pragma unroll
;             for (int m = 0; m < 4; ++m) { const int row = row0 + ai * HALF + m * 16; rinv[m] = rsprev ? rsprev[row] : 1.0f;
; #pragma unroll
;                 for (int bj = 0; bj < 2; ++bj) { const int cx = col0 + bj * HALF; pv[m][bj] = *(const u32x4*)(xs + ((size_t)(cx >> 6) * T + row) * 64 + (cx & 63)); } }
	v_fma_f32 v105, -v166, v104, v167
	v_rcp_f32_e32 v107, v106
	v_fmac_f32_e32 v104, v105, v197
	v_fma_f32 v105, -v166, v104, v167
	s_mov_b64 vcc, s[16:17]
	v_div_fmas_f32 v104, v105, v197, v104
	v_div_fixup_f32 v196, v104, v110, 1.0
	v_fma_f32 v104, -v106, v107, 1.0
	v_fmac_f32_e32 v107, v104, v107
	v_div_scale_f32 v104, vcc, 1.0, v111, 1.0
	v_mul_f32_e32 v105, v104, v107
	v_div_scale_f32 v154, s[0:1], v148, v148, 1.0
	v_fma_f32 v108, -v106, v105, v104
	v_rcp_f32_e32 v155, v154
	v_fmac_f32_e32 v105, v108, v107
	v_fma_f32 v104, -v106, v105, v104
	v_div_fmas_f32 v104, v104, v107, v105
	v_div_fixup_f32 v197, v104, v111, 1.0
	global_load_dwordx4 v[104:107], v[152:153], off offset:528
	global_load_dwordx4 v[108:111], v[152:153], off offset:512
	v_fma_f32 v152, -v154, v155, 1.0
	v_fmac_f32_e32 v155, v152, v155
	v_div_scale_f32 v152, vcc, 1.0, v148, 1.0
	v_mul_f32_e32 v153, v152, v155
	v_fma_f32 v156, -v154, v153, v152
	v_fmac_f32_e32 v153, v156, v155
	v_fma_f32 v152, -v154, v153, v152
	v_div_scale_f32 v154, s[0:1], v149, v149, 1.0
	v_rcp_f32_e32 v156, v154
	v_div_fmas_f32 v152, v152, v155, v153
	v_div_fixup_f32 v188, v152, v148, 1.0
	v_fma_f32 v148, -v154, v156, 1.0
	v_fmac_f32_e32 v156, v148, v156
	v_div_scale_f32 v148, vcc, 1.0, v149, 1.0
	v_mul_f32_e32 v152, v148, v156
	v_fma_f32 v153, -v154, v152, v148
	v_fmac_f32_e32 v152, v153, v156
	v_div_scale_f32 v153, s[0:1], v150, v150, 1.0
	v_fma_f32 v148, -v154, v152, v148
	v_rcp_f32_e32 v154, v153
	v_div_fmas_f32 v148, v148, v156, v152
	v_div_fixup_f32 v189, v148, v149, 1.0
	v_fma_f32 v148, -v153, v154, 1.0
	v_fmac_f32_e32 v154, v148, v154
	v_div_scale_f32 v148, vcc, 1.0, v150, 1.0
	v_mul_f32_e32 v149, v148, v154
	v_fma_f32 v152, -v153, v149, v148
	v_fmac_f32_e32 v149, v152, v154
	v_div_scale_f32 v152, s[0:1], v151, v151, 1.0
	v_fma_f32 v148, -v153, v149, v148
	v_rcp_f32_e32 v153, v152
	v_div_fmas_f32 v148, v148, v154, v149
	v_div_fixup_f32 v198, v148, v150, 1.0
	v_fma_f32 v148, -v152, v153, 1.0
	v_fmac_f32_e32 v153, v148, v153
	v_div_scale_f32 v148, vcc, 1.0, v151, 1.0
	v_mul_f32_e32 v149, v148, v153
	v_fma_f32 v150, -v152, v149, v148
	v_fmac_f32_e32 v149, v150, v153
	v_div_scale_f32 v150, s[0:1], v144, v144, 1.0
	v_fma_f32 v148, -v152, v149, v148
	v_rcp_f32_e32 v152, v150
	v_div_fmas_f32 v148, v148, v153, v149
	v_div_fixup_f32 v199, v148, v151, 1.0
	v_div_scale_f32 v153, s[0:1], v145, v145, 1.0
	v_fma_f32 v148, -v150, v152, 1.0
	v_fmac_f32_e32 v152, v148, v152
	v_div_scale_f32 v148, vcc, 1.0, v144, 1.0
	v_mul_f32_e32 v149, v148, v152
	v_fma_f32 v151, -v150, v149, v148
	v_fmac_f32_e32 v149, v151, v152
	v_fma_f32 v148, -v150, v149, v148
	v_rcp_f32_e32 v154, v153
	v_div_fmas_f32 v148, v148, v152, v149
	v_div_fixup_f32 v200, v148, v144, 1.0
	v_bitop3_b32 v148, s57, 56, v217 bitop3:0xc8
	v_lshlrev_b32_e32 v176, 1, v148
	s_ashr_i32 s0, s57, 6
	v_fma_f32 v144, -v153, v154, 1.0
	v_lshl_add_u64 v[204:205], s[36:37], 0, v[176:177]
	s_ashr_i32 s1, s0, 31
	v_fmac_f32_e32 v154, v144, v154
	v_div_scale_f32 v144, vcc, 1.0, v145, 1.0
	s_lshl_b64 s[12:13], s[0:1], 21
	v_lshl_add_u64 v[148:149], v[204:205], 0, v[214:215]
	v_mul_f32_e32 v152, v144, v154
	v_lshl_add_u64 v[150:151], v[148:149], 0, s[12:13]
	global_load_dwordx4 v[226:229], v[150:151], off
	v_fma_f32 v150, -v153, v152, v144
	v_fmac_f32_e32 v152, v150, v154
	v_div_scale_f32 v150, s[8:9], v146, v146, 1.0
	v_rcp_f32_e32 v151, v150
	v_fma_f32 v144, -v153, v152, v144
	v_div_fmas_f32 v144, v144, v154, v152
	v_div_fixup_f32 v201, v144, v145, 1.0
	v_fma_f32 v144, -v150, v151, 1.0
	v_fmac_f32_e32 v151, v144, v151
	v_div_scale_f32 v144, vcc, 1.0, v146, 1.0
	v_mul_f32_e32 v145, v144, v151
	v_fma_f32 v152, -v150, v145, v144
	v_fmac_f32_e32 v145, v152, v151
	v_fma_f32 v144, -v150, v145, v144
	v_div_scale_f32 v150, s[8:9], v147, v147, 1.0
	v_rcp_f32_e32 v152, v150
	v_div_fmas_f32 v144, v144, v151, v145
	v_div_fixup_f32 v202, v144, v146, 1.0
	s_or_b32 s0, s0, 2
	v_fma_f32 v144, -v150, v152, 1.0
	v_fmac_f32_e32 v152, v144, v152
	v_div_scale_f32 v144, vcc, 1.0, v147, 1.0
	v_mul_f32_e32 v145, v144, v152
	v_fma_f32 v146, -v150, v145, v144
	v_fmac_f32_e32 v145, v146, v152
	v_fma_f32 v144, -v150, v145, v144
	s_ashr_i32 s1, s0, 31
	v_div_fmas_f32 v144, v144, v152, v145
	s_lshl_b64 s[14:15], s[0:1], 21
	v_div_fixup_f32 v203, v144, v147, 1.0
	v_lshl_add_u64 v[144:145], v[148:149], 0, s[14:15]
	global_load_dwordx4 v[230:233], v[144:145], off
	v_and_b32_e32 v144, 64, v222
	v_xor_b32_e32 v146, 16, v222
	v_add_u32_e32 v144, 64, v144
	v_cmp_lt_i32_e32 vcc, v146, v144
	s_lshl_b32 s0, s66, 2
	s_ashr_i32 s1, s0, 31
	v_cndmask_b32_e32 v145, v222, v146, vcc
	v_lshlrev_b32_e32 v224, 2, v145
	v_xor_b32_e32 v145, 32, v222
	v_cmp_lt_i32_e32 vcc, v145, v144
	s_add_u32 s8, s36, s12
	s_addc_u32 s9, s37, s13
	v_cndmask_b32_e32 v144, v222, v145, vcc
	v_lshlrev_b32_e32 v223, 2, v144
	v_or_b32_e32 v144, 16, v206
	v_ashrrev_i32_e32 v145, 31, v144
	v_lshlrev_b64 v[212:213], 7, v[144:145]
	v_lshl_add_u64 v[144:145], v[204:205], 0, v[212:213]
	v_lshl_add_u64 v[146:147], v[144:145], 0, s[12:13]
	v_lshl_add_u64 v[144:145], v[144:145], 0, s[14:15]
	global_load_dwordx4 v[164:167], v[146:147], off
	global_load_dwordx4 v[160:163], v[144:145], off
	v_or_b32_e32 v144, 32, v206
	v_ashrrev_i32_e32 v145, 31, v144
	v_lshlrev_b64 v[210:211], 7, v[144:145]
	v_lshl_add_u64 v[144:145], v[204:205], 0, v[210:211]
	v_lshl_add_u64 v[146:147], v[144:145], 0, s[12:13]
	v_lshl_add_u64 v[144:145], v[144:145], 0, s[14:15]
	global_load_dwordx4 v[156:159], v[146:147], off
	global_load_dwordx4 v[152:155], v[144:145], off
	v_or_b32_e32 v144, 48, v206
	v_ashrrev_i32_e32 v145, 31, v144
	v_lshlrev_b64 v[208:209], 7, v[144:145]
	v_lshl_add_u64 v[144:145], v[204:205], 0, v[208:209]
	v_lshl_add_u64 v[146:147], v[144:145], 0, s[12:13]
	v_lshl_add_u64 v[144:145], v[144:145], 0, s[14:15]
	global_load_dwordx4 v[148:151], v[146:147], off
	s_nop 0
	global_load_dwordx4 v[144:147], v[144:145], off
	v_lshl_add_u64 v[234:235], s[8:9], 0, v[214:215]
	v_lshl_add_u64 v[234:235], v[234:235], 0, v[176:177]
	s_add_u32 s10, s36, s14
	s_addc_u32 s11, s37, s15
	s_waitcnt vmcnt(7)
; __device__ __forceinline__ unsigned cvt_pk_bf16(float lo, float hi) { const f32x2 v = {lo, hi}; const bf16x2_t r = __builtin_convertvector(v, bf16x2_t); return __builtin_bit_cast(unsigned, r); }
; __device__ __forceinline__ float bf_lo(unsigned w) { return __uint_as_float(w << 16); }
; __device__ __forceinline__ float bf_hi(unsigned w) { return __uint_as_float(w & 0xffff0000u); }
;     __device__ __forceinline__ void operator()(const Acc& acc, const Unit& u, int wr, int wc, int fr, int fq) const {
;     ...
;             for (int m = 0; m < 4; ++m) { const int row = row0 + ai * HALF + m * 16; const float ri = rsprev ? 1.0f / rinv[m] : 1.0f; float s = 0.f;
; #pragma unroll
;                 for (int bj = 0; bj < 2; ++bj) { const int cx = col0 + bj * HALF; bf16_t* px = xs + ((size_t)(cx >> 6) * T + row) * 64 + (cx & 63); const u32x4 pw = pv[m][bj];
;                     const f32x4 x0 = (f32x4){bf_lo(pw.x), bf_hi(pw.x), bf_lo(pw.y), bf_hi(pw.y)} * gi[bj][0] * ri, x1 = (f32x4){bf_lo(pw.z), bf_hi(pw.z), bf_lo(pw.w), bf_hi(pw.w)} * gi[bj][1] * ri;
;                     const f32x4 y0 = x0 + acc[ai][bj][m][0] * alpha, y1 = x1 + acc[ai][bj][m][1] * alpha;
;                     s += (y0[0] * y0[0] + y0[1] * y0[1]) + (y0[2] * y0[2] + y0[3] * y0[3]) + (y1[0] * y1[0] + y1[1] * y1[1]) + (y1[2] * y1[2] + y1[3] * y1[3]);
;                     const f32x4 a = y0 * gv[bj][0], b = y1 * gv[bj][1]; u32x4 w; w.x = cvt_pk_bf16(a[0], a[1]); w.y = cvt_pk_bf16(a[2], a[3]); w.z = cvt_pk_bf16(b[0], b[1]); w.w = cvt_pk_bf16(b[2], b[3]);
;                     *(u32x4*)px = w; }
;                 s += __shfl_xor(s, 16); s += __shfl_xor(s, 32);
;                 if (fq == 0) ss[(size_t)row * 32 + u.pn * 4 + wc] = s; }
	v_lshlrev_b32_e32 v236, 16, v226
	v_and_b32_e32 v237, 0xffff0000, v226
	v_lshlrev_b32_e32 v226, 16, v227
	v_and_b32_e32 v227, 0xffff0000, v227
	v_pk_mul_f32 v[236:237], v[190:191], v[236:237]
	v_pk_mul_f32 v[226:227], v[194:195], v[226:227]
	v_lshlrev_b32_e32 v238, 16, v228
	v_and_b32_e32 v239, 0xffff0000, v228
	v_pk_fma_f32 v[142:143], v[142:143], 0.5, v[226:227] op_sel_hi:[1,0,1]
	v_pk_fma_f32 v[140:141], v[140:141], 0.5, v[236:237] op_sel_hi:[1,0,1]
	v_pk_mul_f32 v[238:239], v[192:193], v[238:239]
	v_mul_f32_e32 v225, v141, v141
	v_mul_f32_e32 v226, v143, v143
	v_lshlrev_b32_e32 v228, 16, v229
	v_and_b32_e32 v229, 0xffff0000, v229
	v_pk_fma_f32 v[136:137], v[136:137], 0.5, v[238:239] op_sel_hi:[1,0,1]
	v_fmac_f32_e32 v225, v140, v140
	v_fmac_f32_e32 v226, v142, v142
	v_pk_mul_f32 v[228:229], v[196:197], v[228:229]
	v_add_f32_e32 v225, v225, v226
	v_mul_f32_e32 v226, v137, v137
	v_pk_fma_f32 v[138:139], v[138:139], 0.5, v[228:229] op_sel_hi:[1,0,1]
	v_fmac_f32_e32 v226, v136, v136
	v_add_f32_e32 v225, v226, v225
	v_mul_f32_e32 v226, v139, v139
	v_fmac_f32_e32 v226, v138, v138
	v_add_f32_e32 v225, v226, v225
	v_pk_mul_f32 v[142:143], v[86:87], v[142:143]
	v_pk_mul_f32 v[140:141], v[84:85], v[140:141]
	v_pk_mul_f32 v[226:227], v[82:83], v[138:139]
	v_pk_mul_f32 v[138:139], v[80:81], v[136:137]
	v_cvt_pk_bf16_f32 v136, v140, v141
	v_cvt_pk_bf16_f32 v137, v142, v143
	v_cvt_pk_bf16_f32 v138, v138, v139
	v_cvt_pk_bf16_f32 v139, v226, v227
	global_store_dwordx4 v[234:235], v[136:139], off
	s_waitcnt vmcnt(7)
	v_lshlrev_b32_e32 v140, 16, v231
	v_and_b32_e32 v141, 0xffff0000, v231
	v_lshlrev_b32_e32 v138, 16, v230
	v_and_b32_e32 v139, 0xffff0000, v230
	v_pk_mul_f32 v[138:139], v[188:189], v[138:139]
	v_pk_mul_f32 v[140:141], v[198:199], v[140:141]
	v_lshlrev_b32_e32 v142, 16, v232
	v_and_b32_e32 v143, 0xffff0000, v232
	v_pk_fma_f32 v[134:135], v[134:135], 0.5, v[140:141] op_sel_hi:[1,0,1]
	v_pk_fma_f32 v[132:133], v[132:133], 0.5, v[138:139] op_sel_hi:[1,0,1]
	v_pk_mul_f32 v[142:143], v[200:201], v[142:143]
	v_mul_f32_e32 v138, v133, v133
	v_mul_f32_e32 v139, v135, v135
	v_lshlrev_b32_e32 v226, 16, v233
	v_and_b32_e32 v227, 0xffff0000, v233
	v_pk_fma_f32 v[128:129], v[128:129], 0.5, v[142:143] op_sel_hi:[1,0,1]
	v_fmac_f32_e32 v138, v132, v132
	v_fmac_f32_e32 v139, v134, v134
	v_pk_mul_f32 v[226:227], v[202:203], v[226:227]
	v_add_f32_e32 v138, v138, v139
	v_mul_f32_e32 v139, v129, v129
	v_pk_fma_f32 v[130:131], v[130:131], 0.5, v[226:227] op_sel_hi:[1,0,1]
	v_fmac_f32_e32 v139, v128, v128
	v_add_f32_e32 v138, v139, v138
	v_mul_f32_e32 v139, v131, v131
	v_fmac_f32_e32 v139, v130, v130
	v_add_f32_e32 v138, v139, v138
	v_add_f32_e32 v142, v225, v138
	ds_bpermute_b32 v143, v224, v142
	v_pk_mul_f32 v[140:141], v[104:105], v[128:129]
	v_lshl_add_u64 v[136:137], s[10:11], 0, v[214:215]
	v_pk_mul_f32 v[134:135], v[110:111], v[134:135]
	v_pk_mul_f32 v[132:133], v[108:109], v[132:133]
	s_waitcnt lgkmcnt(0)
	v_add_f32_e32 v128, v142, v143
	ds_bpermute_b32 v129, v223, v128
	v_pk_mul_f32 v[138:139], v[106:107], v[130:131]
	v_lshl_add_u64 v[136:137], v[136:137], 0, v[176:177]
	v_cvt_pk_bf16_f32 v130, v132, v133
	v_cvt_pk_bf16_f32 v131, v134, v135
	v_cvt_pk_bf16_f32 v132, v140, v141
	v_cvt_pk_bf16_f32 v133, v138, v139
	global_store_dwordx4 v[136:137], v[130:133], off
	s_and_saveexec_b64 s[16:17], s[4:5]
	s_cbranch_execz .LBB0_1159
	v_lshl_add_u64 v[130:131], s[20:21], 0, v[214:215]
	v_lshl_add_u64 v[130:131], s[0:1], 2, v[130:131]
	s_lshl_b32 s22, s33, 2
	v_lshl_add_u64 v[130:131], v[130:131], 0, s[22:23]
	s_waitcnt lgkmcnt(0)
	v_add_f32_e32 v128, v128, v129
	global_store_dword v[130:131], v128, off

; __global__ void __launch_bounds__(NTHR, 2) fwd_megakernel(Params p) {
	.amdhsa_kernel _Z14fwd_megakernel6Params
		.amdhsa_group_segment_fixed_size 0
		.amdhsa_private_segment_fixed_size 0
		.amdhsa_kernarg_size 464
		.amdhsa_user_sgpr_count 2
		.amdhsa_user_sgpr_dispatch_ptr 0
		.amdhsa_user_sgpr_queue_ptr 0
		.amdhsa_user_sgpr_kernarg_segment_ptr 1
		.amdhsa_user_sgpr_dispatch_id 0
		.amdhsa_user_sgpr_kernarg_preload_length 0
		.amdhsa_user_sgpr_kernarg_preload_offset 0
		.amdhsa_user_sgpr_private_segment_size 0
		.amdhsa_uses_dynamic_stack 0
		.amdhsa_enable_private_segment 0
		.amdhsa_system_sgpr_workgroup_id_x 1
		.amdhsa_system_sgpr_workgroup_id_y 0
		.amdhsa_system_sgpr_workgroup_id_z 0
		.amdhsa_system_sgpr_workgroup_info 0
		.amdhsa_system_vgpr_workitem_id 2
		.amdhsa_next_free_vgpr 252
		.amdhsa_next_free_sgpr 102
		.amdhsa_accum_offset 252
		.amdhsa_reserve_vcc 1
		.amdhsa_float_round_mode_32 0
		.amdhsa_float_round_mode_16_64 0
		.amdhsa_float_denorm_mode_32 3
		.amdhsa_float_denorm_mode_16_64 3
		.amdhsa_dx10_clamp 1
		.amdhsa_ieee_mode 1
		.amdhsa_fp16_overflow 0
		.amdhsa_tg_split 0
		.amdhsa_exception_fp_ieee_invalid_op 0
		.amdhsa_exception_fp_denorm_src 0
		.amdhsa_exception_fp_ieee_div_zero 0
		.amdhsa_exception_fp_ieee_overflow 0
		.amdhsa_exception_fp_ieee_underflow 0
		.amdhsa_exception_fp_ieee_inexact 0
		.amdhsa_exception_int_div_zero 0
	.end_amdhsa_kernel

; __global__ void __launch_bounds__(NTHR, 2) fwd_megakernel(Params p) {
amdhsa.kernels:
  - .agpr_count:     0
    .args:
      - .offset:         0
        .size:           208
        .value_kind:     by_value
      - .offset:         208
        .size:           4
        .value_kind:     hidden_block_count_x
      - .offset:         212
        .size:           4
        .value_kind:     hidden_block_count_y
      - .offset:         216
        .size:           4
        .value_kind:     hidden_block_count_z
      - .offset:         220
        .size:           2
        .value_kind:     hidden_group_size_x
      - .offset:         222
        .size:           2
        .value_kind:     hidden_group_size_y
      - .offset:         224
        .size:           2
        .value_kind:     hidden_group_size_z
      - .offset:         226
        .size:           2
        .value_kind:     hidden_remainder_x
      - .offset:         228
        .size:           2
        .value_kind:     hidden_remainder_y
      - .offset:         230
        .size:           2
        .value_kind:     hidden_remainder_z
      - .offset:         248
        .size:           8
        .value_kind:     hidden_global_offset_x
      - .offset:         256
        .size:           8
        .value_kind:     hidden_global_offset_y
      - .offset:         264
        .size:           8
        .value_kind:     hidden_global_offset_z
      - .offset:         272
        .size:           2
        .value_kind:     hidden_grid_dims
      - .offset:         296
        .size:           8
        .value_kind:     hidden_multigrid_sync_arg
      - .offset:         328
        .size:           4
        .value_kind:     hidden_dynamic_lds_size
    .group_segment_fixed_size: 0
    .kernarg_segment_align: 8
    .kernarg_segment_size: 464
    .language:       OpenCL C
    .language_version:
      - 2
      - 0
    .max_flat_workgroup_size: 512
    .name:           _Z14fwd_megakernel6Params
    .private_segment_fixed_size: 0
    .sgpr_count:     108
    .sgpr_spill_count: 74
    .symbol:         _Z14fwd_megakernel6Params.kd
    .uniform_work_group_size: 1
    .uses_dynamic_stack: false
    .vgpr_count:     252
    .vgpr_spill_count: 0
    .wavefront_size: 64
